# P1 epilogue: straight-line path for the plain (no activation) memory-query tiles (on v48)
# speedup vs baseline: 1.0062x; 1.0062x over previous
; __device__ __forceinline__ float shx(float v, int m, int lane) { return __int_as_float(__builtin_amdgcn_ds_bpermute((lane ^ m) << 2, __float_as_int(v))); }
; __device__ __forceinline__ float sigm(float v) { return __builtin_amdgcn_rcpf(1.f + __builtin_amdgcn_exp2f(-LOG2E * v)); }
; __device__ __forceinline__ float silu(float v) { return v * sigm(v); }
;     __device__ __forceinline__ void operator()(const f32x4 (&acc)[2][2][4][2], const pg8::Unit& u, int wr, int wc, int fr, int fq) const {
;     ...
;         bf16_t* dst; int ldc, col, act = 0; float* sq = nullptr;
;         if (pn < 18)      { dst = cq;    ldc = 512;  col = (pn - 16) * 256; sq = ssq + (pn - 16) * 4 + wc; }
;         else if (pn < 20) { dst = ckv;   ldc = 512;  col = (pn - 18) * 256; sq = ssq + (size_t)TB * 8 + (pn - 18) * 4 + wc; }
;         else if (pn < 29) { dst = mlazs; ldc = 2048; col = (pn - 21) * 256; act = 1; }
;         else if (pn < 33) { dst = memq;  ldc = 1024; col = (pn - 29) * 256; }
;         else if (pn < 37) { dst = memzs; ldc = 1024; col = (pn - 33) * 256; act = 1; }
;         else { const int g = (pn - 37) >> 3; dst = gates + (size_t)g * TB * 2048; ldc = 2048; col = ((pn - 37) & 7) * 256; act = 2; }
;         dst += col + wc * 32 + 8 * fq;
; #pragma unroll
;         for (int ai = 0; ai < 2; ++ai)
; #pragma unroll
;             for (int m = 0; m < 4; ++m) {
;                 const int row = row0 + ai * 128 + m * 16; float s = 0.f;
; #pragma unroll
;                 for (int bj = 0; bj < 2; ++bj) {
;                     f32x4 v0 = acc[ai][bj][m][0], v1 = acc[ai][bj][m][1];
;                     if (act == 1) {
; #pragma unroll
;                         for (int j = 0; j < 4; ++j) { v0[j] = silu(v0[j]); v1[j] = silu(v1[j]); }
;                     } else if (act == 2) {
; #pragma unroll
;                         for (int j = 0; j < 4; ++j) { v0[j] = sigm(v0[j]); v1[j] = sigm(v1[j]); }
;                     } else {
; #pragma unroll
;                         for (int j = 0; j < 4; ++j) s += v0[j] * v0[j] + v1[j] * v1[j];
;                     }
;                     *(u32x4*)(dst + (size_t)row * ldc + bj * 128) = pk8(v0, v1);
;                 }
;                 if (sq) { const int ln = fr + 16 * fq; s += shx(s, 16, ln); s += shx(s, 32, ln); if (fq == 0) sq[(size_t)row * 8] = s; }
.LBB0_507:
	s_and_b64 vcc, exec, s[6:7]
	s_cbranch_vccnz .Lepi1_sigm
	s_and_b64 vcc, exec, s[10:11]
	s_cbranch_vccnz .Lepi1_silu
	s_cmp_eq_u64 s[36:37], 0
	s_cbranch_scc1 .Lepi1_plain
	s_xor_b64 s[6:7], s[6:7], -1
	s_xor_b64 s[10:11], s[10:11], -1
	v_cndmask_b32_e64 v128, 0, 1, s[6:7]
	s_mov_b64 s[34:35], -1
	s_and_b64 vcc, exec, s[10:11]
	v_cmp_ne_u32_e64 s[6:7], 1, v128
	s_cbranch_vccz .LBB0_513
	s_and_b64 vcc, exec, s[6:7]
	s_cbranch_vccnz .LBB0_510
	v_pk_mul_f32 v[148:149], v[120:121], v[120:121]
	v_pk_mul_f32 v[128:129], v[122:123], v[122:123]
	v_pk_fma_f32 v[148:149], v[124:125], v[124:125], v[148:149]
	v_pk_fma_f32 v[128:129], v[126:127], v[126:127], v[128:129]
	v_add_f32_e32 v131, v148, v149
	v_add_f32_e32 v128, v128, v131
	v_add_f32_e32 v158, v129, v128
	s_mov_b64 s[34:35], 0

; __device__ __forceinline__ float sigm(float v) { return __builtin_amdgcn_rcpf(1.f + __builtin_amdgcn_exp2f(-LOG2E * v)); }
; __device__ __forceinline__ float silu(float v) { return v * sigm(v); }
; __device__ __forceinline__ u32x4 pk8(const f32x4& a, const f32x4& b) { u32x4 w; w.x = pk(a[0], a[1]); w.y = pk(a[2], a[3]); w.z = pk(b[0], b[1]); w.w = pk(b[2], b[3]); return w; }
;     __device__ __forceinline__ void operator()(const f32x4 (&acc)[2][2][4][2], const pg8::Unit& u, int wr, int wc, int fr, int fq) const {
;     ...
;         else if (pn < 33) { dst = memq;  ldc = 1024; col = (pn - 29) * 256; }
;     ...
;         dst += col + wc * 32 + 8 * fq;
; #pragma unroll
;         for (int ai = 0; ai < 2; ++ai)
; #pragma unroll
;             for (int m = 0; m < 4; ++m) {
;                 const int row = row0 + ai * 128 + m * 16; float s = 0.f;
; #pragma unroll
;                 for (int bj = 0; bj < 2; ++bj) {
;                     f32x4 v0 = acc[ai][bj][m][0], v1 = acc[ai][bj][m][1];
;                     if (act == 1) {
; #pragma unroll
;                         for (int j = 0; j < 4; ++j) { v0[j] = silu(v0[j]); v1[j] = silu(v1[j]); }
;                     } else if (act == 2) {
; #pragma unroll
;                         for (int j = 0; j < 4; ++j) { v0[j] = sigm(v0[j]); v1[j] = sigm(v1[j]); }
;                     } else {
; #pragma unroll
;                         for (int j = 0; j < 4; ++j) s += v0[j] * v0[j] + v1[j] * v1[j];
;                     }
;                     *(u32x4*)(dst + (size_t)row * ldc + bj * 128) = pk8(v0, v1);
;                 }
.Lepi1_plain:
	v_add_u32_e32 v128, s2, v162
	v_ashrrev_i32_e32 v129, 31, v128
	v_lshl_add_u64 v[128:129], v[128:129], 1, s[8:9]
	s_lshl_b32 s98, s46, 5
	s_mov_b32 s99, 0
	s_mul_i32 s100, s46, 0xa0
	s_mov_b32 s101, 0
	v_mad_u64_u32 v[148:149], s[2:3], s46, v130, 0
	v_lshl_add_u64 v[148:149], v[148:149], 1, v[128:129]
	v_cvt_pk_bf16_f32 v166, v124, v125
	v_cvt_pk_bf16_f32 v167, v126, v127
	v_cvt_pk_bf16_f32 v168, v120, v121
	v_cvt_pk_bf16_f32 v169, v122, v123
	global_store_dwordx4 v[148:149], v[166:169], off
	v_cvt_pk_bf16_f32 v174, v116, v117
	v_cvt_pk_bf16_f32 v175, v118, v119
	v_cvt_pk_bf16_f32 v176, v112, v113
	v_cvt_pk_bf16_f32 v177, v114, v115
	global_store_dwordx4 v[148:149], v[174:177], off offset:256
	v_lshl_add_u64 v[148:149], v[148:149], 0, s[98:99]
	v_cvt_pk_bf16_f32 v166, v108, v109
	v_cvt_pk_bf16_f32 v167, v110, v111
	v_cvt_pk_bf16_f32 v168, v104, v105
	v_cvt_pk_bf16_f32 v169, v106, v107
	global_store_dwordx4 v[148:149], v[166:169], off
	v_cvt_pk_bf16_f32 v174, v100, v101
	v_cvt_pk_bf16_f32 v175, v102, v103
	v_cvt_pk_bf16_f32 v176, v96, v97
	v_cvt_pk_bf16_f32 v177, v98, v99
	global_store_dwordx4 v[148:149], v[174:177], off offset:256
	v_lshl_add_u64 v[148:149], v[148:149], 0, s[98:99]
	v_cvt_pk_bf16_f32 v166, v92, v93
	v_cvt_pk_bf16_f32 v167, v94, v95
	v_cvt_pk_bf16_f32 v168, v88, v89
	v_cvt_pk_bf16_f32 v169, v90, v91
	global_store_dwordx4 v[148:149], v[166:169], off
	v_cvt_pk_bf16_f32 v174, v84, v85
	v_cvt_pk_bf16_f32 v175, v86, v87
	v_cvt_pk_bf16_f32 v176, v80, v81
	v_cvt_pk_bf16_f32 v177, v82, v83
	global_store_dwordx4 v[148:149], v[174:177], off offset:256
	v_lshl_add_u64 v[148:149], v[148:149], 0, s[98:99]
	v_cvt_pk_bf16_f32 v166, v76, v77
	v_cvt_pk_bf16_f32 v167, v78, v79
	v_cvt_pk_bf16_f32 v168, v72, v73
	v_cvt_pk_bf16_f32 v169, v74, v75
	global_store_dwordx4 v[148:149], v[166:169], off
	v_cvt_pk_bf16_f32 v174, v68, v69
	v_cvt_pk_bf16_f32 v175, v70, v71
	v_cvt_pk_bf16_f32 v176, v64, v65
	v_cvt_pk_bf16_f32 v177, v66, v67
	global_store_dwordx4 v[148:149], v[174:177], off offset:256
	v_lshl_add_u64 v[148:149], v[148:149], 0, s[100:101]
	v_cvt_pk_bf16_f32 v166, v60, v61
	v_cvt_pk_bf16_f32 v167, v62, v63
	v_cvt_pk_bf16_f32 v168, v56, v57
	v_cvt_pk_bf16_f32 v169, v58, v59
	global_store_dwordx4 v[148:149], v[166:169], off
	v_cvt_pk_bf16_f32 v174, v52, v53
	v_cvt_pk_bf16_f32 v175, v54, v55
	v_cvt_pk_bf16_f32 v176, v48, v49
	v_cvt_pk_bf16_f32 v177, v50, v51
	global_store_dwordx4 v[148:149], v[174:177], off offset:256
	v_lshl_add_u64 v[148:149], v[148:149], 0, s[98:99]
	v_cvt_pk_bf16_f32 v166, v44, v45
	v_cvt_pk_bf16_f32 v167, v46, v47
	v_cvt_pk_bf16_f32 v168, v40, v41
	v_cvt_pk_bf16_f32 v169, v42, v43
	global_store_dwordx4 v[148:149], v[166:169], off
	v_cvt_pk_bf16_f32 v174, v36, v37
	v_cvt_pk_bf16_f32 v175, v38, v39
	v_cvt_pk_bf16_f32 v176, v32, v33
	v_cvt_pk_bf16_f32 v177, v34, v35
	global_store_dwordx4 v[148:149], v[174:177], off offset:256
	v_lshl_add_u64 v[148:149], v[148:149], 0, s[98:99]
	v_cvt_pk_bf16_f32 v166, v28, v29
	v_cvt_pk_bf16_f32 v167, v30, v31
	v_cvt_pk_bf16_f32 v168, v24, v25
	v_cvt_pk_bf16_f32 v169, v26, v27
	global_store_dwordx4 v[148:149], v[166:169], off
	v_cvt_pk_bf16_f32 v174, v20, v21
	v_cvt_pk_bf16_f32 v175, v22, v23
	v_cvt_pk_bf16_f32 v176, v16, v17
	v_cvt_pk_bf16_f32 v177, v18, v19
	global_store_dwordx4 v[148:149], v[174:177], off offset:256
	v_lshl_add_u64 v[148:149], v[148:149], 0, s[98:99]
	v_cvt_pk_bf16_f32 v166, v12, v13
	v_cvt_pk_bf16_f32 v167, v14, v15
	v_cvt_pk_bf16_f32 v168, v8, v9
	v_cvt_pk_bf16_f32 v169, v10, v11
	global_store_dwordx4 v[148:149], v[166:169], off
	v_cvt_pk_bf16_f32 v174, v4, v5
	v_cvt_pk_bf16_f32 v175, v6, v7
	v_cvt_pk_bf16_f32 v176, v0, v1
	v_cvt_pk_bf16_f32 v177, v2, v3
	global_store_dwordx4 v[148:149], v[174:177], off offset:256
	s_branch .LBB0_802
